# B1: cross-attention q fragment loads hoisted before the first barrier; redundant barrier before the queue hand-off removed
# baseline (speedup 1.0000x reference)
.LBB0_330:
	s_or_b64 exec, exec, s[0:1]
	s_movk_i32 s0, 0x407
	v_cmp_lt_i32_e32 vcc, s0, v206
	s_and_saveexec_b64 s[0:1], vcc
	s_xor_b64 s[96:97], exec, s[0:1]
	s_cbranch_execz .LBB0_405
	s_movk_i32 s0, 0x447
	v_cmp_lt_u32_e32 vcc, s0, v206
	s_and_saveexec_b64 s[0:1], vcc
	s_xor_b64 s[56:57], exec, s[0:1]
	s_cbranch_execz .LBB0_364
	s_movk_i32 s0, 0x64b
	v_cmp_lt_u32_e32 vcc, s0, v206
	s_and_saveexec_b64 s[0:1], vcc
	s_xor_b64 s[0:1], exec, s[0:1]
	s_cbranch_execz .LBB0_334
	v_add_u32_e32 v48, 0xfffff9b4, v206
	v_lshrrev_b32_e32 v50, 6, v48
	v_bfe_u32 v51, v48, 4, 2
	v_lshl_add_u32 v0, v50, 2, s37
	v_or_b32_e32 v0, v0, v51
	v_ashrrev_i32_e32 v1, 31, v0
	v_readlane_b32 s20, v214, 37
	v_mov_b32_e32 v49, v133
	v_lshlrev_b64 v[0:1], 15, v[0:1]
	v_readlane_b32 s21, v214, 38
	s_nop 0
	v_lshlrev_b32_e32 v4, 4, v49
	v_lshl_add_u64 v[2:3], s[20:21], 0, v[0:1]
	v_readlane_b32 s20, v214, 39
	v_readlane_b32 s21, v214, 40
	v_and_b32_e32 v64, 0x70, v4
	v_lshl_add_u64 v[24:25], v[2:3], 0, v[64:65]
	v_lshl_add_u64 v[0:1], s[20:21], 0, v[0:1]
	v_add_u32_e32 v32, 0, v64
	v_and_b32_e32 v64, 0x1f0, v4
	v_ashrrev_i32_e32 v33, 3, v49
	v_lshl_add_u64 v[28:29], v[0:1], 0, v[64:65]
	v_lshlrev_b32_e32 v0, 6, v33
	v_ashrrev_i32_e32 v41, 5, v49
	v_add_u32_e32 v12, 0x200, v49
	v_ashrrev_i32_e32 v1, 31, v0
	v_lshlrev_b32_e32 v4, 8, v41
	v_ashrrev_i32_e32 v36, 3, v12
	v_lshl_add_u64 v[0:1], v[0:1], 1, v[24:25]
	v_ashrrev_i32_e32 v5, 31, v4
	v_lshlrev_b32_e32 v8, 6, v36
	v_ashrrev_i32_e32 v44, 5, v12
	v_add_u32_e32 v20, 0x400, v49
	v_readlane_b32 s20, v214, 12
	v_readlane_b32 s21, v214, 13
	v_lshlrev_b32_e32 v109, 7, v48
	v_lshlrev_b32_e32 v108, 11, v50
	v_and_b32_e32 v109, 0x780, v109
	v_ashrrev_i32_e32 v110, 2, v49
	v_and_b32_e32 v110, -16, v110
	v_and_b32_e32 v111, 15, v49
	v_or3_b32 v108, v108, v109, v111
	v_add_u32_e32 v108, v108, v110
	v_mul_lo_u32 v108, v108, s83
	v_lshl_add_u32 v108, v51, 7, v108
	v_bfe_u32 v109, v49, 4, 2
	v_lshl_add_u32 v108, v109, 4, v108
	v_add_u32_e32 v108, 0x1500, v108
	global_load_dwordx4 v[112:115], v108, s[20:21]
	global_load_dwordx4 v[116:119], v108, s[20:21] offset:64
	s_barrier
	global_load_dwordx4 v[0:3], v[0:1], off
	v_lshl_add_u64 v[4:5], v[4:5], 1, v[28:29]
	v_ashrrev_i32_e32 v9, 31, v8
	v_lshlrev_b32_e32 v12, 8, v44
	v_ashrrev_i32_e32 v38, 3, v20
	global_load_dwordx4 v[4:7], v[4:5], off
	v_lshl_add_u64 v[8:9], v[8:9], 1, v[24:25]
	v_ashrrev_i32_e32 v13, 31, v12
	v_lshlrev_b32_e32 v16, 6, v38
	v_ashrrev_i32_e32 v46, 5, v20
	v_add_u32_e32 v30, 0x600, v49
	global_load_dwordx4 v[8:11], v[8:9], off
	v_lshl_add_u64 v[12:13], v[12:13], 1, v[28:29]
	v_ashrrev_i32_e32 v17, 31, v16
	v_lshlrev_b32_e32 v20, 8, v46
	v_ashrrev_i32_e32 v40, 3, v30
	global_load_dwordx4 v[12:15], v[12:13], off
	v_lshl_add_u64 v[16:17], v[16:17], 1, v[24:25]
	v_ashrrev_i32_e32 v21, 31, v20
	v_lshlrev_b32_e32 v26, 6, v40
	v_ashrrev_i32_e32 v52, 5, v30
	global_load_dwordx4 v[16:19], v[16:17], off
	v_lshl_add_u64 v[20:21], v[20:21], 1, v[28:29]
	v_ashrrev_i32_e32 v27, 31, v26
	v_lshlrev_b32_e32 v30, 8, v52
	global_load_dwordx4 v[20:23], v[20:21], off
	v_lshl_add_u64 v[24:25], v[26:27], 1, v[24:25]
	v_ashrrev_i32_e32 v31, 31, v30
	global_load_dwordx4 v[24:27], v[24:25], off
	v_lshl_add_u64 v[28:29], v[30:31], 1, v[28:29]
	global_load_dwordx4 v[28:31], v[28:29], off
	s_movk_i32 s22, 0x90
	v_mad_u64_u32 v[34:35], s[20:21], v33, s22, v[32:33]
	v_mad_u64_u32 v[36:37], s[20:21], v36, s22, v[32:33]
	v_mad_u64_u32 v[38:39], s[20:21], v38, s22, v[32:33]
	v_mad_u64_u32 v[32:33], s[20:21], v40, s22, v[32:33]
	v_add_u32_e32 v40, 0, v64
	v_mad_u64_u32 v[42:43], s[20:21], v41, s26, v[40:41]
	v_mad_u64_u32 v[44:45], s[20:21], v44, s26, v[40:41]
	v_mad_u64_u32 v[46:47], s[20:21], v46, s26, v[40:41]
	v_mad_u64_u32 v[40:41], s[20:21], v52, s26, v[40:41]
	v_and_b32_e32 v74, 15, v49
	v_readlane_b32 s20, v214, 12
	v_readlane_b32 s21, v214, 13
	v_bfe_u32 v71, v49, 4, 2
	v_lshlrev_b32_e32 v64, 7, v51
	s_movk_i32 s2, 0x1000
	s_movk_i32 s79, 0x90
	s_waitcnt vmcnt(7)
	ds_write_b128 v34, v[0:3]
	s_waitcnt vmcnt(6)
	ds_write_b128 v42, v[4:7] offset:36864
	s_waitcnt vmcnt(5)
	ds_write_b128 v36, v[8:11]
	s_waitcnt vmcnt(4)
	ds_write_b128 v44, v[12:15] offset:36864
	s_waitcnt vmcnt(3)
	ds_write_b128 v38, v[16:19]
	s_waitcnt vmcnt(2)
	ds_write_b128 v46, v[20:23] offset:36864
	s_waitcnt vmcnt(1)
	ds_write_b128 v32, v[24:27]
	s_waitcnt vmcnt(0)
	ds_write_b128 v40, v[28:31] offset:36864
	v_lshlrev_b32_e32 v1, 7, v48
	v_lshlrev_b32_e32 v0, 11, v50
	v_and_b32_e32 v1, 0x780, v1
	v_ashrrev_i32_e32 v2, 2, v49
	v_and_b32_e32 v2, -16, v2
	v_or3_b32 v0, v0, v1, v74
	v_add_u32_e32 v70, v0, v2
	v_mov_b64_e32 v[0:1], s[20:21]
	v_mad_i64_i32 v[0:1], s[20:21], v70, s83, v[0:1]
	v_lshlrev_b32_e32 v4, 4, v71
	v_mov_b32_e32 v5, v65
	v_lshl_add_u64 v[72:73], v[0:1], 0, v[64:65]
	v_lshl_add_u64 v[36:37], v[72:73], 0, v[4:5]
	v_add_co_u32_e32 v0, vcc, s2, v36
	s_waitcnt lgkmcnt(0)
	s_nop 0
	v_addc_co_u32_e32 v1, vcc, 0, v37, vcc
	s_barrier
	v_mov_b32_e32 v0, v112
	v_mov_b32_e32 v1, v113
	v_mov_b32_e32 v2, v114
	v_mov_b32_e32 v3, v115
	s_mov_b64 s[20:21], 0x1500
	v_lshl_add_u64 v[36:37], v[36:37], 0, s[20:21]
	v_mov_b32_e32 v66, v116
	v_mov_b32_e32 v67, v117
	v_mov_b32_e32 v68, v118
	v_mov_b32_e32 v69, v119
	v_add_u32_e32 v75, 0, v4
	v_mad_u32_u24 v104, v74, s22, v75
	ds_read_b128 v[36:39], v104 offset:18432
	ds_read_b128 v[4:7], v104
	ds_read_b128 v[8:11], v104 offset:2304
	ds_read_b128 v[12:15], v104 offset:4608
	ds_read_b128 v[16:19], v104 offset:6912
	ds_read_b128 v[20:23], v104 offset:9216
	ds_read_b128 v[24:27], v104 offset:11520
	ds_read_b128 v[28:31], v104 offset:13824
	ds_read_b128 v[32:35], v104 offset:16128
	s_mov_b32 s20, 0xf149f2ca
	s_movk_i32 s73, 0x1000
	s_waitcnt lgkmcnt(8)
	v_mfma_f32_16x16x32_bf16 v[76:79], v[36:39], v[0:3], 0
	ds_read_b128 v[36:39], v104 offset:20736
	s_waitcnt lgkmcnt(0)
	v_mfma_f32_16x16x32_bf16 v[80:83], v[36:39], v[0:3], 0
	ds_read_b128 v[36:39], v104 offset:23040
	s_waitcnt lgkmcnt(0)
	v_mfma_f32_16x16x32_bf16 v[84:87], v[36:39], v[0:3], 0
	ds_read_b128 v[36:39], v104 offset:25344
	s_waitcnt lgkmcnt(0)
	v_mfma_f32_16x16x32_bf16 v[88:91], v[36:39], v[0:3], 0
	ds_read_b128 v[36:39], v104 offset:27648
	s_waitcnt lgkmcnt(0)
	v_mfma_f32_16x16x32_bf16 v[92:95], v[36:39], v[0:3], 0
	ds_read_b128 v[36:39], v104 offset:29952
	s_waitcnt lgkmcnt(0)
	v_mfma_f32_16x16x32_bf16 v[96:99], v[36:39], v[0:3], 0
	ds_read_b128 v[36:39], v104 offset:32256
	s_waitcnt lgkmcnt(0)
	v_mfma_f32_16x16x32_bf16 v[100:103], v[36:39], v[0:3], 0
	ds_read_b128 v[36:39], v104 offset:64
	v_mfma_f32_16x16x32_bf16 v[4:7], v[4:7], v[0:3], 0
	s_waitcnt lgkmcnt(0)
	v_mfma_f32_16x16x32_bf16 v[60:63], v[36:39], v[66:69], v[4:7]
	s_nop 5
	ds_read_b128 v[4:7], v104 offset:2368
	v_mfma_f32_16x16x32_bf16 v[8:11], v[8:11], v[0:3], 0
	s_waitcnt lgkmcnt(0)
	v_mfma_f32_16x16x32_bf16 v[56:59], v[4:7], v[66:69], v[8:11]
	ds_read_b128 v[4:7], v104 offset:4672
	v_mfma_f32_16x16x32_bf16 v[12:15], v[12:15], v[0:3], 0
	s_waitcnt lgkmcnt(0)
	v_mfma_f32_16x16x32_bf16 v[52:55], v[4:7], v[66:69], v[12:15]
	ds_read_b128 v[4:7], v104 offset:6976
	v_mfma_f32_16x16x32_bf16 v[16:19], v[16:19], v[0:3], 0
	s_waitcnt lgkmcnt(0)
	v_mfma_f32_16x16x32_bf16 v[48:51], v[4:7], v[66:69], v[16:19]
	ds_read_b128 v[4:7], v104 offset:9280
	v_mfma_f32_16x16x32_bf16 v[20:23], v[20:23], v[0:3], 0
	s_waitcnt lgkmcnt(0)
	v_mfma_f32_16x16x32_bf16 v[44:47], v[4:7], v[66:69], v[20:23]
	ds_read_b128 v[4:7], v104 offset:11584
	v_mfma_f32_16x16x32_bf16 v[24:27], v[24:27], v[0:3], 0
	s_waitcnt lgkmcnt(0)
	v_mfma_f32_16x16x32_bf16 v[40:43], v[4:7], v[66:69], v[24:27]
	ds_read_b128 v[4:7], v104 offset:13888
	v_mfma_f32_16x16x32_bf16 v[28:31], v[28:31], v[0:3], 0
	s_waitcnt lgkmcnt(0)
	v_mfma_f32_16x16x32_bf16 v[36:39], v[4:7], v[66:69], v[28:31]
	ds_read_b128 v[4:7], v104 offset:16192
	v_mfma_f32_16x16x32_bf16 v[32:35], v[32:35], v[0:3], 0
	s_waitcnt lgkmcnt(0)
	v_mfma_f32_16x16x32_bf16 v[32:35], v[4:7], v[66:69], v[32:35]
	ds_read_b128 v[4:7], v104 offset:18496
	s_waitcnt lgkmcnt(0)
	v_mfma_f32_16x16x32_bf16 v[28:31], v[4:7], v[66:69], v[76:79]
	ds_read_b128 v[4:7], v104 offset:20800
	s_nop 1
	ds_read_b128 v[76:79], v104 offset:34560
	s_waitcnt lgkmcnt(1)
	v_mfma_f32_16x16x32_bf16 v[24:27], v[4:7], v[66:69], v[80:83]
	ds_read_b128 v[4:7], v104 offset:23104
	s_waitcnt lgkmcnt(1)
	v_mfma_f32_16x16x32_bf16 v[0:3], v[76:79], v[0:3], 0
	ds_read_b128 v[76:79], v104 offset:34624
	s_waitcnt lgkmcnt(1)
	v_mfma_f32_16x16x32_bf16 v[20:23], v[4:7], v[66:69], v[84:87]
	ds_read_b128 v[4:7], v104 offset:25408
	s_waitcnt lgkmcnt(0)
	v_mfma_f32_16x16x32_bf16 v[16:19], v[4:7], v[66:69], v[88:91]
	ds_read_b128 v[4:7], v104 offset:27712
	s_waitcnt lgkmcnt(0)
	v_mfma_f32_16x16x32_bf16 v[12:15], v[4:7], v[66:69], v[92:95]
	ds_read_b128 v[4:7], v104 offset:30016
	s_waitcnt lgkmcnt(0)
	v_mfma_f32_16x16x32_bf16 v[8:11], v[4:7], v[66:69], v[96:99]
	ds_read_b128 v[4:7], v104 offset:32320
	s_waitcnt lgkmcnt(0)
	v_mfma_f32_16x16x32_bf16 v[4:7], v[4:7], v[66:69], v[100:103]
	v_mfma_f32_16x16x32_bf16 v[0:3], v[76:79], v[66:69], v[0:3]
	v_max_f32_e32 v66, v63, v63
	v_max_f32_e32 v67, v62, v62
	v_max_f32_e32 v66, v67, v66
	v_max_f32_e32 v67, v59, v59
	v_max_f32_e32 v68, v58, v58
	v_max_f32_e32 v67, v68, v67
	v_max3_f32 v66, v60, v61, v66
	v_max3_f32 v67, v56, v57, v67
	v_max3_f32 v66, v66, s20, v67
	v_max_f32_e32 v67, v55, v55
	v_max_f32_e32 v68, v54, v54
	v_max_f32_e32 v67, v68, v67
	v_max_f32_e32 v68, v51, v51
	v_max_f32_e32 v69, v50, v50
	v_max_f32_e32 v68, v69, v68
	v_max3_f32 v67, v52, v53, v67
	v_max3_f32 v68, v48, v49, v68
	v_max3_f32 v66, v66, v67, v68
	v_max_f32_e32 v67, v47, v47
	v_max_f32_e32 v68, v46, v46
	v_max_f32_e32 v67, v68, v67
	v_max_f32_e32 v68, v43, v43
	v_max_f32_e32 v69, v42, v42
	v_max_f32_e32 v68, v69, v68
	v_max3_f32 v67, v44, v45, v67
	v_max3_f32 v68, v40, v41, v68
	v_max3_f32 v66, v66, v67, v68
	v_max_f32_e32 v67, v39, v39
	v_max_f32_e32 v68, v38, v38
	v_max_f32_e32 v67, v68, v67
	v_max_f32_e32 v68, v35, v35
	v_max_f32_e32 v69, v34, v34
	v_max_f32_e32 v68, v69, v68
	v_max3_f32 v67, v36, v37, v67
	v_max3_f32 v68, v32, v33, v68
	v_max3_f32 v66, v66, v67, v68
	v_max_f32_e32 v67, v31, v31
	v_max_f32_e32 v68, v30, v30
	v_max_f32_e32 v67, v68, v67
	v_max_f32_e32 v68, v27, v27
	v_max_f32_e32 v69, v26, v26
	v_max_f32_e32 v68, v69, v68
	v_max3_f32 v67, v28, v29, v67
	v_max3_f32 v68, v24, v25, v68
	v_max3_f32 v66, v66, v67, v68
	v_max_f32_e32 v67, v23, v23
	v_max_f32_e32 v68, v22, v22
	v_max_f32_e32 v67, v68, v67
	v_max_f32_e32 v68, v19, v19
	v_max_f32_e32 v69, v18, v18
	v_max_f32_e32 v68, v69, v68
	v_max3_f32 v67, v20, v21, v67
	v_max3_f32 v68, v16, v17, v68
	v_max3_f32 v66, v66, v67, v68
	v_max_f32_e32 v67, v15, v15
	v_max_f32_e32 v68, v14, v14
	v_max_f32_e32 v67, v68, v67
	v_max_f32_e32 v68, v11, v11
	v_max_f32_e32 v69, v10, v10
	v_max_f32_e32 v68, v69, v68
	v_max3_f32 v67, v12, v13, v67
	v_max3_f32 v68, v8, v9, v68
	v_max3_f32 v66, v66, v67, v68
	v_max_f32_e32 v67, v7, v7
	v_max_f32_e32 v68, v6, v6
	v_max_f32_e32 v67, v68, v67
	v_max_f32_e32 v68, v3, v3
	v_max_f32_e32 v69, v2, v2
	v_max_f32_e32 v68, v69, v68
	v_max3_f32 v67, v4, v5, v67
	v_max3_f32 v68, v0, v1, v68
	v_max3_f32 v66, v66, v67, v68
	v_and_b32_e32 v68, 64, v192
	v_xor_b32_e32 v67, 16, v192
	v_add_u32_e32 v68, 64, v68
	v_cmp_lt_i32_e32 vcc, v67, v68
	s_mov_b64 s[20:21], 0x1700
	s_nop 0
	v_cndmask_b32_e32 v67, v192, v67, vcc
	v_lshlrev_b32_e32 v69, 2, v67
	ds_bpermute_b32 v67, v69, v66
	s_waitcnt lgkmcnt(0)
	v_max_f32_e32 v67, v67, v67
	v_max_f32_e32 v67, v66, v67
	v_xor_b32_e32 v66, 32, v192
	v_cmp_lt_i32_e32 vcc, v66, v68
	s_nop 1
	v_cndmask_b32_e32 v66, v192, v66, vcc
	v_lshlrev_b32_e32 v68, 2, v66
	ds_bpermute_b32 v76, v68, v67
	v_lshlrev_b32_e32 v66, 3, v71
	s_waitcnt lgkmcnt(0)
	v_max_f32_e32 v71, v76, v76
	v_max_f32_e32 v71, v67, v71
	v_sub_f32_e32 v60, v60, v71
	v_mul_f32_e32 v60, 0x3e000000, v60
	v_mul_f32_e32 v60, 0x3fb8aa3b, v60
	v_exp_f32_e32 v78, v60
	v_sub_f32_e32 v60, v61, v71
	v_sub_f32_e32 v56, v56, v71
	v_mul_f32_e32 v60, 0x3e000000, v60
	v_mul_f32_e32 v56, 0x3e000000, v56
	v_mul_f32_e32 v60, 0x3fb8aa3b, v60
	v_mul_f32_e32 v56, 0x3fb8aa3b, v56
	v_exp_f32_e32 v79, v60
	v_sub_f32_e32 v60, v62, v71
	v_exp_f32_e32 v80, v56
	v_sub_f32_e32 v56, v57, v71
	v_sub_f32_e32 v52, v52, v71
	v_mul_f32_e32 v60, 0x3e000000, v60
	v_mul_f32_e32 v56, 0x3e000000, v56
	v_mul_f32_e32 v52, 0x3e000000, v52
	v_mul_f32_e32 v60, 0x3fb8aa3b, v60
	v_mul_f32_e32 v56, 0x3fb8aa3b, v56
	v_mul_f32_e32 v52, 0x3fb8aa3b, v52
	v_exp_f32_e32 v62, v60
	v_sub_f32_e32 v60, v63, v71
	v_exp_f32_e32 v81, v56
	v_sub_f32_e32 v56, v58, v71
	v_exp_f32_e32 v94, v52
	v_sub_f32_e32 v52, v53, v71
	v_mul_f32_e32 v60, 0x3e000000, v60
	v_mul_f32_e32 v56, 0x3e000000, v56
	v_mul_f32_e32 v52, 0x3e000000, v52
	v_mul_f32_e32 v60, 0x3fb8aa3b, v60
	v_mul_f32_e32 v56, 0x3fb8aa3b, v56
	v_mul_f32_e32 v52, 0x3fb8aa3b, v52
	v_exp_f32_e32 v63, v60
	v_exp_f32_e32 v86, v56
	v_sub_f32_e32 v56, v59, v71
	v_exp_f32_e32 v95, v52
	v_sub_f32_e32 v52, v54, v71
	v_sub_f32_e32 v40, v40, v71
	v_mul_f32_e32 v56, 0x3e000000, v56
	v_mul_f32_e32 v52, 0x3e000000, v52
	v_sub_f32_e32 v48, v48, v71
	v_mul_f32_e32 v40, 0x3e000000, v40
	v_add_f32_e32 v60, v78, v79
	v_mul_f32_e32 v56, 0x3fb8aa3b, v56
	v_mul_f32_e32 v52, 0x3fb8aa3b, v52
	v_mul_f32_e32 v48, 0x3e000000, v48
	v_mul_f32_e32 v40, 0x3fb8aa3b, v40
	v_add_f32_e32 v60, v62, v60
	v_exp_f32_e32 v59, v56
	v_exp_f32_e32 v98, v52
	v_sub_f32_e32 v52, v55, v71
	v_mul_f32_e32 v48, 0x3fb8aa3b, v48
	v_exp_f32_e32 v103, v40
	v_sub_f32_e32 v40, v41, v71
	v_add_f32_e32 v61, v63, v60
	v_mul_f32_e32 v52, 0x3e000000, v52
	v_exp_f32_e32 v60, v48
	v_sub_f32_e32 v48, v49, v71
	v_mul_f32_e32 v40, 0x3e000000, v40
	v_add_f32_e32 v56, v80, v81
	v_mul_f32_e32 v52, 0x3fb8aa3b, v52
	v_mul_f32_e32 v48, 0x3e000000, v48
	v_mul_f32_e32 v40, 0x3fb8aa3b, v40
	v_add_f32_e32 v56, v86, v56
	v_exp_f32_e32 v99, v52
	v_mul_f32_e32 v48, 0x3fb8aa3b, v48
	v_exp_f32_e32 v104, v40
	v_sub_f32_e32 v40, v42, v71
	v_add_f32_e32 v53, v59, v56
	v_exp_f32_e32 v56, v48
	v_sub_f32_e32 v48, v50, v71
	v_mul_f32_e32 v40, 0x3e000000, v40
	v_add_f32_e32 v52, v94, v95
	v_mul_f32_e32 v48, 0x3e000000, v48
	v_sub_f32_e32 v44, v44, v71
	v_mul_f32_e32 v40, 0x3fb8aa3b, v40
	v_add_f32_e32 v52, v98, v52
	v_mul_f32_e32 v48, 0x3fb8aa3b, v48
	v_mul_f32_e32 v44, 0x3e000000, v44
	v_exp_f32_e32 v105, v40
	v_sub_f32_e32 v40, v43, v71
	v_add_f32_e32 v55, v99, v52
	v_exp_f32_e32 v52, v48
	v_sub_f32_e32 v48, v51, v71
	v_mul_f32_e32 v44, 0x3fb8aa3b, v44
	v_mul_f32_e32 v40, 0x3e000000, v40
	v_mul_f32_e32 v48, 0x3e000000, v48
	v_exp_f32_e32 v100, v44
	v_sub_f32_e32 v44, v45, v71
	v_mul_f32_e32 v40, 0x3fb8aa3b, v40
	v_mul_f32_e32 v48, 0x3fb8aa3b, v48
	v_mul_f32_e32 v44, 0x3e000000, v44
	v_exp_f32_e32 v106, v40
	v_exp_f32_e32 v54, v48
	v_mul_f32_e32 v44, 0x3fb8aa3b, v44
	v_sub_f32_e32 v32, v32, v71
	v_mov_b32_e32 v57, v65
	v_exp_f32_e32 v45, v44
	v_sub_f32_e32 v44, v46, v71
	v_add_f32_e32 v40, v103, v104
	v_mul_f32_e32 v32, 0x3e000000, v32
	v_pk_add_f32 v[48:49], v[60:61], v[56:57]
	v_mul_f32_e32 v44, 0x3e000000, v44
	v_add_f32_e32 v40, v105, v40
	v_mul_f32_e32 v32, 0x3fb8aa3b, v32
	v_pk_add_f32 v[48:49], v[52:53], v[48:49]
	v_mul_f32_e32 v44, 0x3fb8aa3b, v44
	v_add_f32_e32 v43, v106, v40
	v_exp_f32_e32 v40, v32
	v_sub_f32_e32 v32, v33, v71
	v_pk_add_f32 v[48:49], v[54:55], v[48:49]
	v_exp_f32_e32 v101, v44
	v_sub_f32_e32 v44, v47, v71
	v_mul_f32_e32 v32, 0x3e000000, v32
	v_pk_add_f32 v[48:49], v[48:49], v[48:49] op_sel_hi:[0,1]
	v_mul_f32_e32 v44, 0x3e000000, v44
	v_mul_f32_e32 v32, 0x3fb8aa3b, v32
	v_mul_f32_e32 v44, 0x3fb8aa3b, v44
	v_sub_f32_e32 v36, v36, v71
	v_exp_f32_e32 v48, v32
	v_sub_f32_e32 v32, v34, v71
	v_sub_f32_e32 v24, v24, v71
	v_exp_f32_e32 v102, v44
	v_mul_f32_e32 v36, 0x3e000000, v36
	v_mul_f32_e32 v32, 0x3e000000, v32
	v_mul_f32_e32 v24, 0x3e000000, v24
	v_mul_f32_e32 v36, 0x3fb8aa3b, v36
	v_mul_f32_e32 v32, 0x3fb8aa3b, v32
	v_mul_f32_e32 v24, 0x3fb8aa3b, v24
	v_add_f32_e32 v44, v100, v45
	v_exp_f32_e32 v57, v36
	v_sub_f32_e32 v36, v37, v71
	v_exp_f32_e32 v42, v32
	v_sub_f32_e32 v32, v35, v71
	v_exp_f32_e32 v47, v24
	v_sub_f32_e32 v24, v25, v71
	v_add_f32_e32 v44, v101, v44
	v_mul_f32_e32 v36, 0x3e000000, v36
	v_mul_f32_e32 v32, 0x3e000000, v32
	v_sub_f32_e32 v28, v28, v71
	v_mul_f32_e32 v24, 0x3e000000, v24
	v_add_f32_e32 v41, v102, v44
	v_mul_f32_e32 v36, 0x3fb8aa3b, v36
	v_mul_f32_e32 v32, 0x3fb8aa3b, v32
	v_mul_f32_e32 v28, 0x3e000000, v28
	v_mul_f32_e32 v24, 0x3fb8aa3b, v24
	v_exp_f32_e32 v58, v36
	v_sub_f32_e32 v36, v38, v71
	v_exp_f32_e32 v34, v32
	v_pk_add_f32 v[32:33], v[40:41], v[48:49]
	v_mul_f32_e32 v28, 0x3fb8aa3b, v28
	v_exp_f32_e32 v49, v24
	v_sub_f32_e32 v24, v26, v71
	v_mul_f32_e32 v36, 0x3e000000, v36
	v_pk_add_f32 v[32:33], v[42:43], v[32:33]
	v_exp_f32_e32 v43, v28
	v_sub_f32_e32 v28, v29, v71
	v_mul_f32_e32 v24, 0x3e000000, v24
	v_mul_f32_e32 v36, 0x3fb8aa3b, v36
	v_mul_f32_e32 v28, 0x3e000000, v28
	v_mul_f32_e32 v24, 0x3fb8aa3b, v24
	v_exp_f32_e32 v53, v36
	v_sub_f32_e32 v36, v39, v71
	v_mul_f32_e32 v28, 0x3fb8aa3b, v28
	v_exp_f32_e32 v50, v24
	v_sub_f32_e32 v24, v27, v71
	v_mul_f32_e32 v36, 0x3e000000, v36
	v_exp_f32_e32 v46, v28
	v_sub_f32_e32 v28, v30, v71
	v_mul_f32_e32 v24, 0x3e000000, v24
	v_mul_f32_e32 v36, 0x3fb8aa3b, v36
	v_mul_f32_e32 v28, 0x3e000000, v28
	v_sub_f32_e32 v29, v31, v71
	v_mul_f32_e32 v24, 0x3fb8aa3b, v24
	v_exp_f32_e32 v55, v36
	v_mul_f32_e32 v28, 0x3fb8aa3b, v28
	v_mul_f32_e32 v29, 0x3e000000, v29
	v_exp_f32_e32 v51, v24
	v_exp_f32_e32 v28, v28
	v_mul_f32_e32 v29, 0x3fb8aa3b, v29
	v_sub_f32_e32 v16, v16, v71
	v_add_f32_e32 v36, v57, v58
	v_exp_f32_e32 v29, v29
	v_add_f32_e32 v24, v47, v49
	v_mul_f32_e32 v16, 0x3e000000, v16
	v_add_f32_e32 v36, v53, v36
	v_add_f32_e32 v24, v50, v24
	v_sub_f32_e32 v21, v21, v71
	v_mul_f32_e32 v16, 0x3fb8aa3b, v16
	v_add_f32_e32 v35, v55, v36
	v_add_f32_e32 v30, v43, v46
	v_add_f32_e32 v27, v51, v24
	v_mul_f32_e32 v21, 0x3e000000, v21
	v_exp_f32_e32 v24, v16
	v_sub_f32_e32 v16, v17, v71
	v_pk_add_f32 v[32:33], v[34:35], v[32:33]
	v_add_f32_e32 v30, v28, v30
	v_mul_f32_e32 v21, 0x3fb8aa3b, v21
	v_mul_f32_e32 v16, 0x3e000000, v16
	v_pk_add_f32 v[32:33], v[32:33], v[32:33] op_sel_hi:[0,1]
	v_add_f32_e32 v25, v29, v30
	v_exp_f32_e32 v30, v21
	v_sub_f32_e32 v21, v22, v71
	v_mul_f32_e32 v16, 0x3fb8aa3b, v16
	v_sub_f32_e32 v20, v20, v71
	v_mul_f32_e32 v21, 0x3e000000, v21
	v_exp_f32_e32 v32, v16
	v_sub_f32_e32 v16, v18, v71
	v_mul_f32_e32 v20, 0x3e000000, v20
	v_mul_f32_e32 v21, 0x3fb8aa3b, v21
	v_mul_f32_e32 v16, 0x3e000000, v16
	v_mul_f32_e32 v20, 0x3fb8aa3b, v20
	v_exp_f32_e32 v22, v21
	v_sub_f32_e32 v21, v23, v71
	v_mul_f32_e32 v16, 0x3fb8aa3b, v16
	v_exp_f32_e32 v20, v20
	v_mul_f32_e32 v21, 0x3e000000, v21
	v_exp_f32_e32 v26, v16
	v_sub_f32_e32 v16, v19, v71
	v_mul_f32_e32 v21, 0x3fb8aa3b, v21
	v_mul_f32_e32 v16, 0x3e000000, v16
	v_exp_f32_e32 v23, v21
	v_mul_f32_e32 v16, 0x3fb8aa3b, v16
	v_exp_f32_e32 v16, v16
	v_add_f32_e32 v21, v20, v30
	v_sub_f32_e32 v12, v12, v71
	v_add_f32_e32 v21, v22, v21
	v_pk_add_f32 v[18:19], v[24:25], v[32:33]
	v_mul_f32_e32 v12, 0x3e000000, v12
	v_add_f32_e32 v17, v23, v21
	v_pk_add_f32 v[18:19], v[26:27], v[18:19]
	v_mul_f32_e32 v12, 0x3fb8aa3b, v12
	v_pk_add_f32 v[36:37], v[16:17], v[18:19]
	v_exp_f32_e32 v18, v12
	v_sub_f32_e32 v12, v13, v71
	v_mul_f32_e32 v12, 0x3e000000, v12
	v_mul_f32_e32 v12, 0x3fb8aa3b, v12
	v_exp_f32_e32 v19, v12
	v_sub_f32_e32 v12, v14, v71
	v_mul_f32_e32 v12, 0x3e000000, v12
	v_sub_f32_e32 v8, v8, v71
	v_mul_f32_e32 v12, 0x3fb8aa3b, v12
	v_mul_f32_e32 v8, 0x3e000000, v8
	v_exp_f32_e32 v25, v12
	v_sub_f32_e32 v12, v15, v71
	v_mul_f32_e32 v8, 0x3fb8aa3b, v8
	v_mul_f32_e32 v12, 0x3e000000, v12
	v_exp_f32_e32 v33, v8
	v_sub_f32_e32 v8, v9, v71
	v_sub_u32_e32 v9, v75, v66
	v_mul_f32_e32 v12, 0x3fb8aa3b, v12
	v_mad_u32_u24 v9, v74, s26, v9
	v_exp_f32_e32 v27, v12
	v_pk_add_f32 v[12:13], v[36:37], v[36:37] op_sel_hi:[0,1]
	v_add_u32_e32 v39, 0x9000, v9
	v_add_u32_e32 v31, 0xb000, v9
	v_add_u32_e32 v35, 0xd000, v9
	v_add_u32_e32 v37, 0xf000, v9
	ds_read2_b64 v[74:77], v39 offset1:4
	ds_read2_b64 v[82:85], v31 offset0:32 offset1:36
	v_cvt_pk_bf16_f32 v80, v80, v81
	v_cvt_pk_bf16_f32 v81, v86, v59
	ds_read2_b64 v[86:89], v35 offset0:64 offset1:68
	ds_read2_b64 v[90:93], v37 offset0:96 offset1:100
	v_mul_f32_e32 v8, 0x3e000000, v8
	v_mul_f32_e32 v8, 0x3fb8aa3b, v8
	v_exp_f32_e32 v36, v8
	v_sub_f32_e32 v8, v10, v71
	v_mul_f32_e32 v8, 0x3e000000, v8
	v_mul_f32_e32 v8, 0x3fb8aa3b, v8
	v_add_f32_e32 v12, v18, v19
	v_exp_f32_e32 v41, v8
	v_sub_f32_e32 v8, v11, v71
	v_add_f32_e32 v12, v25, v12
	v_cvt_pk_bf16_f32 v78, v78, v79
	v_cvt_pk_bf16_f32 v79, v62, v63
	v_mul_f32_e32 v8, 0x3e000000, v8
	v_add_f32_e32 v15, v27, v12
	s_waitcnt lgkmcnt(3)
	v_mfma_f32_16x16x32_bf16 v[74:77], v[74:77], v[78:81], 0
	v_mul_f32_e32 v12, 0x3fb8aa3b, v8
	v_sub_f32_e32 v4, v4, v71
	v_mul_f32_e32 v4, 0x3e000000, v4
	s_waitcnt lgkmcnt(2)
	v_mfma_f32_16x16x32_bf16 v[82:85], v[82:85], v[78:81], 0
	v_mul_f32_e32 v4, 0x3fb8aa3b, v4
	v_exp_f32_e32 v38, v4
	v_sub_f32_e32 v4, v5, v71
	s_waitcnt lgkmcnt(1)
	v_mfma_f32_16x16x32_bf16 v[8:11], v[86:89], v[78:81], 0
	ds_read2_b64 v[86:89], v39 offset0:8 offset1:12
	v_mul_f32_e32 v4, 0x3e000000, v4
	v_mul_f32_e32 v4, 0x3fb8aa3b, v4
	s_waitcnt lgkmcnt(1)
	v_mfma_f32_16x16x32_bf16 v[78:81], v[90:93], v[78:81], 0
	v_cvt_pk_bf16_f32 v92, v60, v56
	ds_read2_b64 v[60:63], v35 offset0:72 offset1:76
	v_cvt_pk_bf16_f32 v90, v94, v95
	ds_read2_b64 v[94:97], v31 offset0:40 offset1:44
	v_cvt_pk_bf16_f32 v91, v98, v99
	v_cvt_pk_bf16_f32 v93, v52, v54
	v_exp_f32_e32 v44, v12
	s_waitcnt lgkmcnt(2)
	v_mfma_f32_16x16x32_bf16 v[74:77], v[86:89], v[90:93], v[74:77]
	ds_read2_b64 v[86:89], v37 offset0:104 offset1:108
	v_add_f32_e32 v12, v33, v36
	v_add_f32_e32 v12, v41, v12
	s_waitcnt lgkmcnt(2)
	v_mfma_f32_16x16x32_bf16 v[8:11], v[60:63], v[90:93], v[8:11]
	ds_read2_b64 v[60:63], v39 offset0:16 offset1:20
	v_sub_f32_e32 v0, v0, v71
	v_add_f32_e32 v17, v44, v12
	s_waitcnt lgkmcnt(2)
	v_mfma_f32_16x16x32_bf16 v[82:85], v[94:97], v[90:93], v[82:85]
	ds_read2_b64 v[94:97], v35 offset0:80 offset1:84
	v_mul_f32_e32 v0, 0x3e000000, v0
	v_mov_b32_e32 v67, v65
	s_waitcnt lgkmcnt(2)
	v_mfma_f32_16x16x32_bf16 v[78:81], v[86:89], v[90:93], v[78:81]
	v_cvt_pk_bf16_f32 v86, v100, v45
	ds_read2_b64 v[90:93], v31 offset0:48 offset1:52
	v_cvt_pk_bf16_f32 v87, v101, v102
	v_cvt_pk_bf16_f32 v88, v103, v104
	v_cvt_pk_bf16_f32 v89, v105, v106
	v_exp_f32_e32 v45, v4
	s_waitcnt lgkmcnt(2)
	v_mfma_f32_16x16x32_bf16 v[60:63], v[60:63], v[86:89], v[74:77]
	v_sub_f32_e32 v4, v6, v71
	v_mul_f32_e32 v4, 0x3e000000, v4
	v_mul_f32_e32 v4, 0x3fb8aa3b, v4
	ds_read2_b64 v[74:77], v37 offset0:112 offset1:116
	s_waitcnt lgkmcnt(1)
	v_mfma_f32_16x16x32_bf16 v[82:85], v[90:93], v[86:89], v[82:85]
	v_exp_f32_e32 v52, v4
	v_sub_f32_e32 v4, v7, v71
	v_mul_f32_e32 v12, 0x3e000000, v4
	v_mfma_f32_16x16x32_bf16 v[8:11], v[94:97], v[86:89], v[8:11]
	v_mul_f32_e32 v12, 0x3fb8aa3b, v12
	v_mul_f32_e32 v0, 0x3fb8aa3b, v0
	v_cvt_pk_bf16_f32 v54, v57, v58
	s_waitcnt lgkmcnt(0)
	v_mfma_f32_16x16x32_bf16 v[74:77], v[74:77], v[86:89], v[78:81]
	ds_read2_b64 v[86:89], v35 offset0:88 offset1:92
	v_cvt_pk_bf16_f32 v55, v53, v55
	v_cvt_pk_bf16_f32 v56, v40, v48
	v_cvt_pk_bf16_f32 v57, v42, v34
	v_exp_f32_e32 v34, v12
	s_nop 0
	ds_read2_b64 v[78:81], v31 offset0:56 offset1:60
	s_waitcnt lgkmcnt(0)
	v_mfma_f32_16x16x32_bf16 v[78:81], v[78:81], v[54:57], v[82:85]
	v_add_f32_e32 v12, v38, v45
	v_exp_f32_e32 v14, v0
	v_sub_f32_e32 v0, v1, v71
	v_mfma_f32_16x16x32_bf16 v[82:85], v[86:89], v[54:57], v[8:11]
	v_cvt_pk_bf16_f32 v11, v50, v51
	v_lshl_add_u64 v[50:51], v[72:73], 0, v[66:67]
	ds_read2_b64 v[90:93], v39 offset0:24 offset1:28
	ds_read2_b64 v[4:7], v37 offset0:120 offset1:124
	v_add_f32_e32 v8, v52, v12
	v_mul_f32_e32 v12, 0x3e000000, v0
	v_add_co_u32_e32 v0, vcc, s2, v50
	v_cvt_pk_bf16_f32 v9, v28, v29
	s_waitcnt lgkmcnt(1)
	v_mfma_f32_16x16x32_bf16 v[58:61], v[90:93], v[54:57], v[60:63]
	v_addc_co_u32_e32 v1, vcc, 0, v51, vcc
	global_load_dwordx2 v[28:29], v[0:1], off offset:1792
	s_waitcnt lgkmcnt(0)
	v_mfma_f32_16x16x32_bf16 v[4:7], v[4:7], v[54:57], v[74:77]
	ds_read2_b64 v[54:57], v31 offset0:64 offset1:68
	ds_read2_b64 v[86:89], v39 offset0:32 offset1:36
	v_add_f32_e32 v21, v34, v8
	v_cvt_pk_bf16_f32 v8, v43, v46
	v_cvt_pk_bf16_f32 v10, v47, v49
	ds_read2_b64 v[46:49], v35 offset0:96 offset1:100
	s_waitcnt lgkmcnt(2)
	v_mfma_f32_16x16x32_bf16 v[54:57], v[54:57], v[8:11], v[78:81]
	ds_read2_b64 v[74:77], v37 offset0:128 offset1:132
	s_nop 1
	ds_read2_b64 v[78:81], v39 offset0:40 offset1:44
	v_mul_f32_e32 v0, 0x3fb8aa3b, v12
	s_waitcnt lgkmcnt(3)
	v_mfma_f32_16x16x32_bf16 v[58:61], v[86:89], v[8:11], v[58:61]
	v_exp_f32_e32 v12, v0
	v_sub_f32_e32 v0, v2, v71
	v_mul_f32_e32 v0, 0x3e000000, v0
	s_waitcnt lgkmcnt(2)
	v_mfma_f32_16x16x32_bf16 v[46:49], v[46:49], v[8:11], v[82:85]
	v_mul_f32_e32 v0, 0x3fb8aa3b, v0
	s_mov_b32 s2, 0x4580000
	s_waitcnt lgkmcnt(1)
	v_mfma_f32_16x16x32_bf16 v[4:7], v[74:77], v[8:11], v[4:7]
	v_cvt_pk_bf16_f32 v8, v20, v30
	ds_read2_b64 v[72:75], v31 offset0:72 offset1:76
	v_cvt_pk_bf16_f32 v9, v22, v23
	v_cvt_pk_bf16_f32 v10, v24, v32
	v_cvt_pk_bf16_f32 v11, v26, v16
	ds_read2_b64 v[82:85], v35 offset0:104 offset1:108
	s_waitcnt lgkmcnt(2)
	v_mfma_f32_16x16x32_bf16 v[58:61], v[78:81], v[8:11], v[58:61]
	ds_read2_b64 v[76:79], v37 offset0:136 offset1:140
	v_exp_f32_e32 v16, v0
	v_sub_f32_e32 v0, v3, v71
	s_waitcnt lgkmcnt(2)
	v_mfma_f32_16x16x32_bf16 v[54:57], v[72:75], v[8:11], v[54:57]
	v_mul_f32_e32 v20, 0x3e000000, v0
	ds_read2_b64 v[72:75], v39 offset0:48 offset1:52
	v_cvt_pk_bf16_f32 v32, v14, v12
	s_waitcnt lgkmcnt(2)
	v_mfma_f32_16x16x32_bf16 v[46:49], v[82:85], v[8:11], v[46:49]
	v_cvt_pk_bf16_f32 v30, v38, v45
	v_ashrrev_i32_e32 v71, 31, v70
	s_waitcnt lgkmcnt(1)
	v_mfma_f32_16x16x32_bf16 v[0:3], v[76:79], v[8:11], v[4:7]
	ds_read2_b64 v[8:11], v31 offset0:80 offset1:84
	v_cvt_pk_bf16_f32 v4, v18, v19
	v_mul_f32_e32 v18, 0x3fb8aa3b, v20
	v_exp_f32_e32 v20, v18
	v_pk_add_f32 v[18:19], v[14:15], v[12:13]
	v_cvt_pk_bf16_f32 v5, v25, v27
	v_cvt_pk_bf16_f32 v6, v33, v36
	v_cvt_pk_bf16_f32 v7, v41, v44
	ds_read2_b64 v[40:43], v35 offset0:112 offset1:116
	s_waitcnt lgkmcnt(1)
	v_mfma_f32_16x16x32_bf16 v[8:11], v[8:11], v[4:7], v[54:57]
	v_add_f32_e64 v18, v16, v18
	v_add_f32_e64 v19, v17, v19
	ds_read2_b64 v[12:15], v35 offset0:120 offset1:124
	v_pk_add_f32 v[18:19], v[20:21], v[18:19]
	ds_read2_b64 v[54:57], v37 offset0:144 offset1:148
	v_add_f32_e32 v17, v18, v19
	v_lshl_add_u64 v[18:19], v[50:51], 0, s[20:21]
	global_load_dwordx2 v[22:23], v[18:19], off offset:32
	ds_bpermute_b32 v21, v69, v17
	v_mfma_f32_16x16x32_bf16 v[24:27], v[72:75], v[4:7], v[58:61]
	v_cvt_pk_bf16_f32 v33, v16, v20
	s_waitcnt lgkmcnt(0)
	v_add_f32_e32 v16, v17, v21
	v_mfma_f32_16x16x32_bf16 v[40:43], v[40:43], v[4:7], v[46:49]
	ds_bpermute_b32 v17, v68, v16
	s_waitcnt lgkmcnt(0)
	v_add_f32_e32 v16, v16, v17
	v_mfma_f32_16x16x32_bf16 v[0:3], v[54:57], v[4:7], v[0:3]
	ds_read2_b64 v[4:7], v31 offset0:88 offset1:92
	v_cvt_pk_bf16_f32 v31, v52, v34
	ds_read2_b64 v[46:49], v39 offset0:56 offset1:60
	s_waitcnt lgkmcnt(1)
	v_mfma_f32_16x16x32_bf16 v[8:11], v[4:7], v[30:33], v[8:11]
	ds_read2_b64 v[34:37], v37 offset0:152 offset1:156
	v_mfma_f32_16x16x32_bf16 v[4:7], v[12:15], v[30:33], v[40:43]
	v_div_scale_f32 v12, s[20:21], v16, v16, 1.0
	v_rcp_f32_e32 v13, v12
	s_waitcnt lgkmcnt(1)
	v_mfma_f32_16x16x32_bf16 v[24:27], v[46:49], v[30:33], v[24:27]
	s_mov_b64 s[20:21], 0x4580600
	v_fma_f32 v14, -v12, v13, 1.0
	v_fmac_f32_e32 v13, v14, v13
	v_div_scale_f32 v14, vcc, 1.0, v16, 1.0
	v_mul_f32_e32 v15, v14, v13
	v_fma_f32 v17, -v12, v15, v14
	v_fmac_f32_e32 v15, v17, v13
	v_fma_f32 v12, -v12, v15, v14
	v_div_fmas_f32 v12, v12, v13, v15
	global_load_dwordx2 v[14:15], v[18:19], off offset:64
	v_div_fixup_f32 v12, v12, v16, 1.0
	v_lshlrev_b64 v[16:17], 11, v[70:71]
	v_lshl_add_u64 v[16:17], s[94:95], 0, v[16:17]
	v_lshl_add_u64 v[20:21], v[16:17], 0, v[64:65]
	s_waitcnt vmcnt(2)
	v_lshlrev_b32_e32 v17, 16, v28
	v_mul_f32_e32 v13, 0xbfb8aa3b, v17
	v_exp_f32_e32 v13, v13
	s_waitcnt lgkmcnt(0)
	v_mfma_f32_16x16x32_bf16 v[0:3], v[34:37], v[30:33], v[0:3]
	v_and_b32_e32 v31, 0xffff0000, v28
	v_mul_f32_e32 v16, 0xbfb8aa3b, v31
	v_add_f32_e32 v13, 1.0, v13
	v_rcp_f32_e32 v13, v13
	v_exp_f32_e32 v28, v16
	v_mov_b32_e32 v16, v24
	v_lshlrev_b32_e32 v33, 16, v29
	v_pk_mul_f32 v[16:17], v[12:13], v[16:17]
	v_add_f32_e32 v13, 1.0, v28
	v_mul_f32_e32 v24, v16, v17
	v_mul_f32_e32 v16, 0xbfb8aa3b, v33
	v_rcp_f32_e32 v13, v13
	v_exp_f32_e32 v28, v16
	v_mov_b32_e32 v30, v25
	v_and_b32_e32 v29, 0xffff0000, v29
	v_pk_mul_f32 v[16:17], v[12:13], v[30:31]
	v_add_f32_e32 v13, 1.0, v28
	v_mul_f32_e32 v16, v16, v17
	v_rcp_f32_e32 v13, v13
	v_mul_f32_e32 v17, 0xbfb8aa3b, v29
	v_exp_f32_e32 v25, v17
	v_mov_b32_e32 v32, v26
	v_cvt_pk_bf16_f32 v24, v24, v16
	v_pk_mul_f32 v[16:17], v[12:13], v[32:33]
	v_add_f32_e32 v13, 1.0, v25
	v_mul_f32_e32 v25, v16, v17
	global_load_dwordx2 v[16:17], v[18:19], off offset:96
	v_rcp_f32_e32 v13, v13
	v_mov_b32_e32 v28, v27
	s_waitcnt vmcnt(2)
	v_lshlrev_b32_e32 v27, 16, v22
	v_lshl_add_u64 v[20:21], v[20:21], 0, v[66:67]
	v_pk_mul_f32 v[18:19], v[12:13], v[28:29]
	v_mov_b32_e32 v26, v8
	v_mul_f32_e32 v13, v18, v19
	v_cvt_pk_bf16_f32 v25, v25, v13
	v_mul_f32_e32 v13, 0xbfb8aa3b, v27
	v_lshl_add_u64 v[18:19], v[20:21], 0, s[20:21]
	v_add_co_u32_e32 v20, vcc, s2, v20
	v_exp_f32_e32 v13, v13
	s_nop 0
	v_addc_co_u32_e32 v21, vcc, 0, v21, vcc
	global_store_dwordx2 v[20:21], v[24:25], off offset:1536
	v_and_b32_e32 v21, 0xffff0000, v22
	v_mul_f32_e32 v20, 0xbfb8aa3b, v21
	v_add_f32_e32 v13, 1.0, v13
	v_exp_f32_e32 v20, v20
	v_rcp_f32_e32 v13, v13
	v_lshlrev_b32_e32 v25, 16, v23
	v_and_b32_e32 v23, 0xffff0000, v23
	v_add_f32_e32 v8, 1.0, v20
	v_pk_mul_f32 v[26:27], v[12:13], v[26:27]
	v_rcp_f32_e32 v13, v8
	v_mul_f32_e32 v8, 0xbfb8aa3b, v25
	v_exp_f32_e32 v22, v8
	v_mov_b32_e32 v20, v9
	v_pk_mul_f32 v[8:9], v[12:13], v[20:21]
	v_mul_f32_e32 v20, 0xbfb8aa3b, v23
	v_add_f32_e32 v13, 1.0, v22
	v_exp_f32_e32 v20, v20
	v_rcp_f32_e32 v13, v13
	v_mov_b32_e32 v24, v10
	v_mul_f32_e32 v21, v8, v9
	v_add_f32_e32 v10, 1.0, v20
	v_pk_mul_f32 v[8:9], v[12:13], v[24:25]
	v_rcp_f32_e32 v13, v10
	v_mov_b32_e32 v22, v11
	v_mul_f32_e32 v20, v8, v9
	v_mul_f32_e32 v26, v26, v27
	v_pk_mul_f32 v[8:9], v[12:13], v[22:23]
	v_cvt_pk_bf16_f32 v10, v26, v21
	s_waitcnt vmcnt(2)
	v_lshlrev_b32_e32 v21, 16, v15
	v_mul_f32_e32 v8, v8, v9
	v_lshlrev_b32_e32 v9, 16, v14
	v_cvt_pk_bf16_f32 v11, v20, v8
	v_mul_f32_e32 v8, 0xbfb8aa3b, v9
	v_exp_f32_e32 v8, v8
	global_store_dwordx2 v[18:19], v[10:11], off offset:32
	v_and_b32_e32 v11, 0xffff0000, v14
	v_and_b32_e32 v15, 0xffff0000, v15
	v_add_f32_e32 v8, 1.0, v8
	v_rcp_f32_e32 v13, v8
	v_mul_f32_e32 v8, 0xbfb8aa3b, v11
	v_exp_f32_e32 v10, v8
	v_mov_b32_e32 v8, v4
	v_pk_mul_f32 v[8:9], v[12:13], v[8:9]
	v_mov_b32_e32 v20, v6
	v_add_f32_e32 v4, 1.0, v10
	v_rcp_f32_e32 v13, v4
	v_mul_f32_e32 v4, 0xbfb8aa3b, v21
	v_exp_f32_e32 v14, v4
	v_mul_f32_e32 v8, v8, v9
	v_mov_b32_e32 v10, v5
	v_pk_mul_f32 v[4:5], v[12:13], v[10:11]
	v_add_f32_e32 v9, 1.0, v14
	v_rcp_f32_e32 v13, v9
	v_mul_f32_e32 v9, 0xbfb8aa3b, v15
	v_exp_f32_e32 v9, v9
	v_mul_f32_e32 v10, v4, v5
	v_pk_mul_f32 v[4:5], v[12:13], v[20:21]
	v_mov_b32_e32 v14, v7
	v_add_f32_e32 v6, 1.0, v9
	v_rcp_f32_e32 v13, v6
	v_cvt_pk_bf16_f32 v6, v8, v10
	v_mul_f32_e32 v8, v4, v5
	v_mov_b32_e32 v10, v3
	v_pk_mul_f32 v[4:5], v[12:13], v[14:15]
	s_waitcnt vmcnt(2)
	v_lshlrev_b32_e32 v9, 16, v17
	v_mul_f32_e32 v4, v4, v5
	v_lshlrev_b32_e32 v5, 16, v16
	v_cvt_pk_bf16_f32 v7, v8, v4
	v_mul_f32_e32 v4, 0xbfb8aa3b, v5
	v_exp_f32_e32 v4, v4
	global_store_dwordx2 v[18:19], v[6:7], off offset:64
	v_and_b32_e32 v7, 0xffff0000, v16
	v_and_b32_e32 v11, 0xffff0000, v17
	v_add_f32_e32 v4, 1.0, v4
	v_rcp_f32_e32 v13, v4
	v_mul_f32_e32 v4, 0xbfb8aa3b, v7
	v_exp_f32_e32 v6, v4
	v_mov_b32_e32 v4, v0
	v_pk_mul_f32 v[4:5], v[12:13], v[4:5]
	v_add_f32_e32 v0, 1.0, v6
	v_rcp_f32_e32 v13, v0
	v_mul_f32_e32 v0, 0xbfb8aa3b, v9
	v_exp_f32_e32 v8, v0
	v_mul_f32_e32 v4, v4, v5
	v_mov_b32_e32 v6, v1
	v_pk_mul_f32 v[0:1], v[12:13], v[6:7]
	v_add_f32_e32 v5, 1.0, v8
	v_rcp_f32_e32 v13, v5
	v_mul_f32_e32 v5, 0xbfb8aa3b, v11
	v_exp_f32_e32 v5, v5
	v_mov_b32_e32 v8, v2
	v_mul_f32_e32 v6, v0, v1
	v_pk_mul_f32 v[0:1], v[12:13], v[8:9]
	v_add_f32_e32 v2, 1.0, v5
	v_rcp_f32_e32 v13, v2
	v_cvt_pk_bf16_f32 v2, v4, v6
	v_mul_f32_e32 v4, v0, v1
	v_pk_mul_f32 v[0:1], v[12:13], v[10:11]
	s_nop 0
	v_mul_f32_e32 v0, v0, v1
	v_cvt_pk_bf16_f32 v3, v4, v0
	global_store_dwordx2 v[18:19], v[2:3], off offset:96

.LBB0_497:
	s_or_b64 exec, exec, s[56:57]
	s_waitcnt lgkmcnt(0)
	s_nop 0
	s_and_saveexec_b64 s[0:1], s[38:39]
	s_cbranch_execz .LBB0_325
	s_mov_b64 s[20:21], src_shared_base
	s_cmp_lg_u32 s24, -1
	s_cselect_b32 s2, s24, 0
	s_cselect_b32 s20, s21, 0
	v_mov_b32_e32 v0, s2
	v_mov_b32_e32 v1, s20
	v_readfirstlane_b32 s20, v206
	s_cmpk_lt_u32 s20, 0x408
	s_cbranch_scc1 .Lmy_q_nowait
	s_waitcnt vmcnt(0)
